# cross-attention phases hand-written: one head per workgroup, whole K/V^T panels LDS-DMA'd once into LDS, 64-key steps with the MoBA fast-path body (no per-step barriers)
# speedup vs baseline: 1.0370x; 1.0053x over previous
; template <int l> __device__ __forceinline__ void layer_body(const Args& args, LAS unsigned char* lds, const XcdBarrier& bar) {
;     ...
;         { const int hd = wave & 3; const float scale2 = 0.08838834764831845f * LOG2E;
;           for (int rep = 0; rep < NREP(7); ++rep) for (int w = bx; w < T / 128; w += G)
;             for (int jj = 0; jj < 2; ++jj) { const int qt = w * 4 + (wave >> 2) * 2 + jj, b = qt >> 7, q0g = qt * 32;
;                 bf16x8 qf[8];
; #pragma unroll
;                 for (int s = 0; s < 8; ++s) qf[s] = *(const bf16x8*)(XQ + (size_t)(q0g + r) * XAW + hd * 128 + 16 * s + 8 * hh);
;                 f32x16 o[4];
; #pragma unroll
;                 for (int dg = 0; dg < 4; ++dg)
; #pragma unroll
;                     for (int i = 0; i < 16; ++i) o[dg][i] = 0.f;
;                 float m_run = -1e30f, l_run = 0.f;
;                 const size_t tb0 = ((size_t)l * 32 + b * 4 + hd) * 8 * 4096;
;                 attn_run<128>(XKP + tb0 + (hh * 32 + pr) * 8, XVP + tb0 + (hh * 128 + r) * 8, 0, 7, qf, o, m_run, l_run, [&](int t, f32x16& st) {
.LBB0_797:
	s_or_b64 exec, exec, s[0:1]
	s_add_u32 s92, s70, 0x11000000
	s_addc_u32 s93, s71, 0
	s_and_b64 vcc, exec, s[6:7]
	s_waitcnt lgkmcnt(0)
	s_barrier
	s_cbranch_vccnz .LBB0_806
	v_readfirstlane_b32 s3, v204
	s_and_b32 s0, s2, 3
	s_lshr_b32 s3, s3, 6
	s_lshr_b32 s1, s2, 2
	s_lshl_b32 s15, s1, 4
	s_lshl_b32 s37, s3, 1
	s_add_i32 s15, s15, s37
	s_lshr_b32 s1, s15, 7
	s_lshl_b32 s1, s1, 2
	s_add_i32 s1, s1, s0
	s_lshl_b32 s1, s1, 16
	s_lshl_b32 s37, s3, 13
	s_add_i32 s1, s1, s37
	s_mov_b32 s36, 0x3e0293ee
	v_and_b32_e32 v2, 63, v204
	v_mov_b32_e32 v7, 0
	v_and_b32_e32 v3, 31, v2
	v_lshrrev_b32_e32 v4, 5, v2
	v_and_b32_e32 v5, 19, v3
	v_and_b32_e32 v6, 4, v3
	v_lshlrev_b32_e32 v6, 1, v6
	v_and_b32_e32 v8, 8, v3
	v_lshrrev_b32_e32 v8, 1, v8
	v_or3_b32 v5, v5, v6, v8
	v_lshl_add_u32 v5, v4, 5, v5
	v_lshlrev_b32_e32 v145, 4, v5
	v_lshl_add_u32 v6, v4, 7, v3
	v_lshlrev_b32_e32 v179, 4, v6
	v_add_u32_e32 v179, 0x8000, v179
	v_mov_b32_e32 v6, v2
	v_lshlrev_b32_e32 v146, 10, v3
	v_lshl_add_u32 v146, v4, 4, v146
	s_add_u32 s10, s70, 0x6800000
	s_addc_u32 s11, s71, 0
	s_add_u32 s10, s10, s1
	s_addc_u32 s11, s11, 0
	v_lshl_add_u64 v[8:9], v[6:7], 4, s[10:11]
	s_mov_b64 s[10:11], 0x1000
	v_lshl_add_u64 v[10:11], v[8:9], 0, s[10:11]
	s_mov_b64 s[10:11], 0x400000
	v_lshl_add_u64 v[12:13], v[8:9], 0, s[10:11]
	v_lshl_add_u64 v[14:15], v[10:11], 0, s[10:11]
	s_mov_b32 m0, s37
	s_nop 0
	global_load_lds_dwordx4 v[8:9], off
	global_load_lds_dwordx4 v[8:9], off offset:1024
	global_load_lds_dwordx4 v[8:9], off offset:2048
	global_load_lds_dwordx4 v[8:9], off offset:3072
	s_add_i32 m0, s37, 0x1000
	s_nop 0
	global_load_lds_dwordx4 v[10:11], off
	global_load_lds_dwordx4 v[10:11], off offset:1024
	global_load_lds_dwordx4 v[10:11], off offset:2048
	global_load_lds_dwordx4 v[10:11], off offset:3072
	s_add_i32 m0, s37, 0x10000
	s_nop 0
	global_load_lds_dwordx4 v[12:13], off
	global_load_lds_dwordx4 v[12:13], off offset:1024
	global_load_lds_dwordx4 v[12:13], off offset:2048
	global_load_lds_dwordx4 v[12:13], off offset:3072
	s_add_i32 m0, s37, 0x11000
	s_nop 0
	global_load_lds_dwordx4 v[14:15], off
	global_load_lds_dwordx4 v[14:15], off offset:1024
	global_load_lds_dwordx4 v[14:15], off offset:2048
	global_load_lds_dwordx4 v[14:15], off offset:3072
	s_lshl_b32 s0, s0, 8
	s_mov_b32 s3, 0
.Lxa0_jj:
	s_add_i32 s1, s15, s3
	s_lshl_b32 s1, s1, 15
	s_add_i32 s1, s1, s0
	v_add_u32_e32 v144, s1, v146
	v_mov_b32_e32 v147, 0
	s_add_u32 s10, s70, 0xf000000
	s_addc_u32 s11, s71, 0
	v_mov_b32_e32 v10, v144
	v_mov_b32_e32 v11, 0
	v_lshl_add_u64 v[8:9], v[10:11], 0, s[10:11]
	global_load_dwordx4 v[112:115], v[8:9], off
	global_load_dwordx4 v[116:119], v[8:9], off offset:32
	global_load_dwordx4 v[120:123], v[8:9], off offset:64
	global_load_dwordx4 v[124:127], v[8:9], off offset:96
	global_load_dwordx4 v[128:131], v[8:9], off offset:128
	global_load_dwordx4 v[132:135], v[8:9], off offset:160
	global_load_dwordx4 v[136:139], v[8:9], off offset:192
	global_load_dwordx4 v[140:143], v[8:9], off offset:224
	v_mov_b32_e32 v16, 0
	v_mov_b32_e32 v17, v16
	v_mov_b32_e32 v18, v16
	v_mov_b32_e32 v19, v16
	v_mov_b32_e32 v20, v16
	v_mov_b32_e32 v21, v16
	v_mov_b32_e32 v22, v16
	v_mov_b32_e32 v23, v16
	v_mov_b32_e32 v24, v16
	v_mov_b32_e32 v25, v16
	v_mov_b32_e32 v26, v16
	v_mov_b32_e32 v27, v16
	v_mov_b32_e32 v28, v16
	v_mov_b32_e32 v29, v16
	v_mov_b32_e32 v30, v16
	v_mov_b32_e32 v31, v16
	v_mov_b32_e32 v32, v16
	v_mov_b32_e32 v33, v16
	v_mov_b32_e32 v34, v16
	v_mov_b32_e32 v35, v16
	v_mov_b32_e32 v36, v16
	v_mov_b32_e32 v37, v16
	v_mov_b32_e32 v38, v16
	v_mov_b32_e32 v39, v16
	v_mov_b32_e32 v40, v16
	v_mov_b32_e32 v41, v16
	v_mov_b32_e32 v42, v16
	v_mov_b32_e32 v43, v16
	v_mov_b32_e32 v44, v16
	v_mov_b32_e32 v45, v16
	v_mov_b32_e32 v46, v16
	v_mov_b32_e32 v47, v16
	v_mov_b32_e32 v48, v16
	v_mov_b32_e32 v49, v16
	v_mov_b32_e32 v50, v16
	v_mov_b32_e32 v51, v16
	v_mov_b32_e32 v52, v16
	v_mov_b32_e32 v53, v16
	v_mov_b32_e32 v54, v16
	v_mov_b32_e32 v55, v16
	v_mov_b32_e32 v56, v16
	v_mov_b32_e32 v57, v16
	v_mov_b32_e32 v58, v16
	v_mov_b32_e32 v59, v16
	v_mov_b32_e32 v60, v16
	v_mov_b32_e32 v61, v16
	v_mov_b32_e32 v62, v16
	v_mov_b32_e32 v63, v16
	v_mov_b32_e32 v64, v16
	v_mov_b32_e32 v65, v16
	v_mov_b32_e32 v66, v16
	v_mov_b32_e32 v67, v16
	v_mov_b32_e32 v68, v16
	v_mov_b32_e32 v69, v16
	v_mov_b32_e32 v70, v16
	v_mov_b32_e32 v71, v16
	v_mov_b32_e32 v72, v16
	v_mov_b32_e32 v73, v16
	v_mov_b32_e32 v74, v16
	v_mov_b32_e32 v75, v16
	v_mov_b32_e32 v76, v16
	v_mov_b32_e32 v77, v16
	v_mov_b32_e32 v78, v16
	v_mov_b32_e32 v79, v16
	v_mov_b32_e32 v193, 0xf149f2ca
	v_mov_b32_e32 v190, 0
	s_mov_b32 s14, 0
	s_waitcnt vmcnt(0)
	s_cmp_lg_u32 s3, 0
	s_cbranch_scc1 .Lxa0_step
	s_barrier
; #define MFMA32(a, b, c) __builtin_amdgcn_mfma_f32_32x32x16_bf16((a), (b), (c), 0, 0, 0)
; template <int DH, class LF>
; __device__ __forceinline__ void attn_run(const bf16* kb, const bf16* vb, int t0, int t1, const bf16x8 (&qf)[DH / 16], f32x16 (&o)[DH / 32], float& m_run, float& l_run, LF&& lf) {
;     ...
;     for (int t = t0; t <= t1; ++t) {
;         bf16x8 vf[2][ND];
; #pragma unroll
;         for (int s2 = 0; s2 < 2; ++s2)
; #pragma unroll
;             for (int dg = 0; dg < ND; ++dg) vf[s2][dg] = *(const bf16x8*)(vb + s2 * (2 * DH * 8) + dg * 256);
;         f32x16 st;
; #pragma unroll
;         for (int i = 0; i < 16; ++i) st[i] = 0.f;
; #pragma unroll
;         for (int s = 0; s < KS; ++s) st = MFMA32(kf[s], qf[s], st);
;         if (t < t1) kb += TS;
;         vb += TS;
; #pragma unroll
;         for (int s = 0; s < KS; ++s) kf[s] = *(const bf16x8*)(kb + s * 512);
;         lf(t, st);
;         float tmax = fmaxf(fmaxf(st[0], st[1]), st[2]);
; #pragma unroll
;         for (int i = 3; i < 15; i += 2) tmax = fmaxf(fmaxf(tmax, st[i]), st[i + 1]);
;         tmax = fmaxf(tmax, st[15]);
;         { auto rr_ = __builtin_amdgcn_permlane32_swap(__float_as_uint(tmax), __float_as_uint(tmax), false, false); tmax = fmaxf(__uint_as_float(rr_[0]), __uint_as_float(rr_[1])); }
;         if (__any(tmax > m_run + 8.0f)) {
;             const float mn = fmaxf(m_run, tmax), corr = __builtin_amdgcn_exp2f(m_run - mn); m_run = mn; l_run *= corr;
; #pragma unroll
;             for (int dg = 0; dg < ND; ++dg) o[dg] = o[dg] * corr;
;         }
.Lxa0_step:
	v_add_u32_e32 v1, s14, v145
	ds_read_b128 v[218:221], v1
	ds_read_b128 v[222:225], v1 offset:8192
	ds_read_b128 v[226:229], v1 offset:1024
	ds_read_b128 v[230:233], v1 offset:9216
	ds_read_b128 v[234:237], v1 offset:2048
	ds_read_b128 v[238:241], v1 offset:10240
	ds_read_b128 v[242:245], v1 offset:3072
	ds_read_b128 v[246:249], v1 offset:11264
	v_add_u32_e32 v202, s14, v179
	s_waitcnt lgkmcnt(7)
	v_mfma_f32_32x32x16_bf16 v[80:95], v[218:221], v[112:115], 0
	ds_read_b128 v[218:221], v1 offset:4096
	s_waitcnt lgkmcnt(7)
	v_mfma_f32_32x32x16_bf16 v[96:111], v[222:225], v[112:115], 0
	ds_read_b128 v[222:225], v1 offset:12288
	s_waitcnt lgkmcnt(7)
	v_mfma_f32_32x32x16_bf16 v[80:95], v[226:229], v[116:119], v[80:95]
	ds_read_b128 v[226:229], v1 offset:5120
	s_waitcnt lgkmcnt(7)
	v_mfma_f32_32x32x16_bf16 v[96:111], v[230:233], v[116:119], v[96:111]
	ds_read_b128 v[230:233], v1 offset:13312
	s_waitcnt lgkmcnt(7)
	v_mfma_f32_32x32x16_bf16 v[80:95], v[234:237], v[120:123], v[80:95]
	ds_read_b128 v[234:237], v1 offset:6144
	s_waitcnt lgkmcnt(7)
	v_mfma_f32_32x32x16_bf16 v[96:111], v[238:241], v[120:123], v[96:111]
	ds_read_b128 v[238:241], v1 offset:14336
	s_waitcnt lgkmcnt(7)
	v_mfma_f32_32x32x16_bf16 v[80:95], v[242:245], v[124:127], v[80:95]
	ds_read_b128 v[242:245], v1 offset:7168
	s_waitcnt lgkmcnt(7)
	v_mfma_f32_32x32x16_bf16 v[96:111], v[246:249], v[124:127], v[96:111]
	ds_read_b128 v[246:249], v1 offset:15360
	s_waitcnt lgkmcnt(7)
	v_mfma_f32_32x32x16_bf16 v[80:95], v[218:221], v[128:131], v[80:95]
	s_waitcnt lgkmcnt(6)
	v_mfma_f32_32x32x16_bf16 v[96:111], v[222:225], v[128:131], v[96:111]
	s_waitcnt lgkmcnt(5)
	v_mfma_f32_32x32x16_bf16 v[80:95], v[226:229], v[132:135], v[80:95]
	s_waitcnt lgkmcnt(4)
	v_mfma_f32_32x32x16_bf16 v[96:111], v[230:233], v[132:135], v[96:111]
	s_waitcnt lgkmcnt(3)
	v_mfma_f32_32x32x16_bf16 v[80:95], v[234:237], v[136:139], v[80:95]
	s_waitcnt lgkmcnt(2)
	v_mfma_f32_32x32x16_bf16 v[96:111], v[238:241], v[136:139], v[96:111]
	s_waitcnt lgkmcnt(1)
	v_mfma_f32_32x32x16_bf16 v[80:95], v[242:245], v[140:143], v[80:95]
	s_waitcnt lgkmcnt(0)
	v_mfma_f32_32x32x16_bf16 v[96:111], v[246:249], v[140:143], v[96:111]
	ds_read_b128 v[218:221], v202 offset:32768
	ds_read_b128 v[222:225], v202 offset:33280
	ds_read_b128 v[226:229], v202 offset:36864
	ds_read_b128 v[230:233], v202 offset:37376
	ds_read_b128 v[234:237], v202 offset:33792
	ds_read_b128 v[238:241], v202 offset:34304
	ds_read_b128 v[242:245], v202 offset:37888
	ds_read_b128 v[246:249], v202 offset:38400
	v_mov_b32_e32 v2, 0
	s_nop 1
	v_max3_f32 v1, v80, v81, v82
	v_max3_f32 v3, v83, v84, v85
	v_max3_f32 v1, v1, v86, v87
	v_max3_f32 v3, v3, v88, v89
	v_max3_f32 v1, v1, v90, v91
	v_max3_f32 v3, v3, v92, v93
	v_max3_f32 v1, v1, v94, v95
	v_max3_f32 v3, v3, v96, v97
	v_max3_f32 v1, v1, v98, v99
	v_max3_f32 v3, v3, v100, v101
	v_max3_f32 v1, v1, v102, v103
	v_max3_f32 v3, v3, v104, v105
	v_max3_f32 v1, v1, v106, v107
	v_max3_f32 v3, v3, v108, v109
	v_max3_f32 v1, v1, v110, v111
	v_max_f32_e32 v1, v1, v3
	v_fma_f32 v1, v1, s36, v2
	v_mov_b32_e32 v3, v1
	s_nop 1
	v_permlane32_swap_b32_e32 v1, v3
	v_max_f32_e32 v1, v1, v3
	v_add_f32_e32 v3, 0x41000000, v193
	v_cmp_gt_f32_e32 vcc, v1, v3
	s_cbranch_vccz .Lxa0_go
	v_max_f32_e32 v3, v193, v193
	v_max_f32_e32 v1, v3, v1
	v_sub_f32_e32 v4, v193, v1
	v_exp_f32_e32 v4, v4
	v_mov_b32_e32 v193, v1
	v_pk_mul_f32 v[78:79], v[78:79], v[4:5] op_sel_hi:[1,0]
	v_pk_mul_f32 v[76:77], v[76:77], v[4:5] op_sel_hi:[1,0]
	v_pk_mul_f32 v[74:75], v[74:75], v[4:5] op_sel_hi:[1,0]
	v_pk_mul_f32 v[72:73], v[72:73], v[4:5] op_sel_hi:[1,0]
	v_pk_mul_f32 v[70:71], v[70:71], v[4:5] op_sel_hi:[1,0]
	v_pk_mul_f32 v[68:69], v[68:69], v[4:5] op_sel_hi:[1,0]
	v_pk_mul_f32 v[66:67], v[66:67], v[4:5] op_sel_hi:[1,0]
	v_pk_mul_f32 v[64:65], v[64:65], v[4:5] op_sel_hi:[1,0]
	v_pk_mul_f32 v[62:63], v[62:63], v[4:5] op_sel_hi:[1,0]
	v_pk_mul_f32 v[60:61], v[60:61], v[4:5] op_sel_hi:[1,0]
	v_pk_mul_f32 v[58:59], v[58:59], v[4:5] op_sel_hi:[1,0]
	v_pk_mul_f32 v[56:57], v[56:57], v[4:5] op_sel_hi:[1,0]
	v_pk_mul_f32 v[54:55], v[54:55], v[4:5] op_sel_hi:[1,0]
	v_pk_mul_f32 v[52:53], v[52:53], v[4:5] op_sel_hi:[1,0]
	v_pk_mul_f32 v[50:51], v[50:51], v[4:5] op_sel_hi:[1,0]
	v_pk_mul_f32 v[48:49], v[48:49], v[4:5] op_sel_hi:[1,0]
	v_pk_mul_f32 v[46:47], v[46:47], v[4:5] op_sel_hi:[1,0]
	v_pk_mul_f32 v[44:45], v[44:45], v[4:5] op_sel_hi:[1,0]
	v_pk_mul_f32 v[42:43], v[42:43], v[4:5] op_sel_hi:[1,0]
	v_pk_mul_f32 v[40:41], v[40:41], v[4:5] op_sel_hi:[1,0]
	v_pk_mul_f32 v[38:39], v[38:39], v[4:5] op_sel_hi:[1,0]
	v_pk_mul_f32 v[36:37], v[36:37], v[4:5] op_sel_hi:[1,0]
	v_pk_mul_f32 v[34:35], v[34:35], v[4:5] op_sel_hi:[1,0]
	v_pk_mul_f32 v[32:33], v[32:33], v[4:5] op_sel_hi:[1,0]
	v_pk_mul_f32 v[30:31], v[30:31], v[4:5] op_sel_hi:[1,0]
	v_pk_mul_f32 v[28:29], v[28:29], v[4:5] op_sel_hi:[1,0]
	v_pk_mul_f32 v[26:27], v[26:27], v[4:5] op_sel_hi:[1,0]
	v_pk_mul_f32 v[24:25], v[24:25], v[4:5] op_sel_hi:[1,0]
	v_pk_mul_f32 v[22:23], v[22:23], v[4:5] op_sel_hi:[1,0]
	v_pk_mul_f32 v[20:21], v[20:21], v[4:5] op_sel_hi:[1,0]
	v_pk_mul_f32 v[18:19], v[18:19], v[4:5] op_sel_hi:[1,0]
	v_pk_mul_f32 v[16:17], v[16:17], v[4:5] op_sel_hi:[1,0]
	v_mul_f32_e32 v190, v190, v4
; __device__ __forceinline__ unsigned cvtpk(float lo, float hi) { f32x2v_ v = {lo, hi}; bf16x2v_ b = __builtin_convertvector(v, bf16x2v_); return __builtin_bit_cast(unsigned, b); }
; #define MFMA32(a, b, c) __builtin_amdgcn_mfma_f32_32x32x16_bf16((a), (b), (c), 0, 0, 0)
; template <int DH, class LF>
; __device__ __forceinline__ void attn_run(const bf16* kb, const bf16* vb, int t0, int t1, const bf16x8 (&qf)[DH / 16], f32x16 (&o)[DH / 32], float& m_run, float& l_run, LF&& lf) {
;     ...
;         st = st - m_run;
; #pragma unroll
;         for (int i = 0; i < 16; ++i) st[i] = __builtin_amdgcn_exp2f(st[i]);
;         { float ps = ((st[0] + st[1]) + (st[2] + st[3])) + ((st[4] + st[5]) + (st[6] + st[7])) + ((st[8] + st[9]) + (st[10] + st[11])) + ((st[12] + st[13]) + (st[14] + st[15]));
;           { auto rr_ = __builtin_amdgcn_permlane32_swap(__float_as_uint(ps), __float_as_uint(ps), false, false); ps = __uint_as_float(rr_[0]) + __uint_as_float(rr_[1]); } l_run += ps; }
;         v4u p0, p1; p0.x = cvtpk(st[0], st[1]); p0.y = cvtpk(st[2], st[3]); p0.z = cvtpk(st[4], st[5]); p0.w = cvtpk(st[6], st[7]);
;         p1.x = cvtpk(st[8], st[9]); p1.y = cvtpk(st[10], st[11]); p1.z = cvtpk(st[12], st[13]); p1.w = cvtpk(st[14], st[15]);
;         const bf16x8 pf0 = __builtin_bit_cast(bf16x8, p0), pf1 = __builtin_bit_cast(bf16x8, p1);
; #pragma unroll
;         for (int dg = 0; dg < ND; ++dg) { o[dg] = MFMA32(vf[0][dg], pf0, o[dg]); o[dg] = MFMA32(vf[1][dg], pf1, o[dg]); }
;     }
.Lxa0_go:
	v_sub_f32_e32 v3, v2, v193
	v_fma_f32 v80, v80, s36, v3
	v_fma_f32 v81, v81, s36, v3
	v_fma_f32 v82, v82, s36, v3
	v_fma_f32 v83, v83, s36, v3
	v_fma_f32 v84, v84, s36, v3
	v_fma_f32 v85, v85, s36, v3
	v_fma_f32 v86, v86, s36, v3
	v_fma_f32 v87, v87, s36, v3
	v_exp_f32_e32 v80, v80
	v_exp_f32_e32 v81, v81
	v_exp_f32_e32 v82, v82
	v_exp_f32_e32 v83, v83
	v_exp_f32_e32 v84, v84
	v_exp_f32_e32 v85, v85
	v_exp_f32_e32 v86, v86
	v_exp_f32_e32 v87, v87
	v_cvt_pk_bf16_f32 v4, v80, v81
	v_cvt_pk_bf16_f32 v5, v82, v83
	v_cvt_pk_bf16_f32 v6, v84, v85
	v_cvt_pk_bf16_f32 v7, v86, v87
	s_nop 0
	s_waitcnt lgkmcnt(7)
	v_mfma_f32_32x32x16_bf16 v[64:79], v[218:221], v[4:7], v[64:79]
	ds_read_b128 v[218:221], v202 offset:40960
	s_waitcnt lgkmcnt(7)
	v_mfma_f32_32x32x16_bf16 v[48:63], v[222:225], v[4:7], v[48:63]
	ds_read_b128 v[222:225], v202 offset:41472
	v_fma_f32 v88, v88, s36, v3
	v_fma_f32 v89, v89, s36, v3
	v_fma_f32 v90, v90, s36, v3
	v_fma_f32 v91, v91, s36, v3
	v_fma_f32 v92, v92, s36, v3
	v_fma_f32 v93, v93, s36, v3
	v_fma_f32 v94, v94, s36, v3
	v_fma_f32 v95, v95, s36, v3
	v_exp_f32_e32 v88, v88
	v_exp_f32_e32 v89, v89
	v_exp_f32_e32 v90, v90
	v_exp_f32_e32 v91, v91
	v_exp_f32_e32 v92, v92
	v_exp_f32_e32 v93, v93
	v_exp_f32_e32 v94, v94
	v_exp_f32_e32 v95, v95
	v_cvt_pk_bf16_f32 v8, v88, v89
	v_cvt_pk_bf16_f32 v9, v90, v91
	v_cvt_pk_bf16_f32 v10, v92, v93
	v_cvt_pk_bf16_f32 v11, v94, v95
	s_nop 0
	s_waitcnt lgkmcnt(7)
	v_mfma_f32_32x32x16_bf16 v[64:79], v[226:229], v[8:11], v[64:79]
	ds_read_b128 v[226:229], v202 offset:45056
	s_waitcnt lgkmcnt(7)
	v_mfma_f32_32x32x16_bf16 v[48:63], v[230:233], v[8:11], v[48:63]
	ds_read_b128 v[230:233], v202 offset:45568
	s_waitcnt lgkmcnt(7)
	v_mfma_f32_32x32x16_bf16 v[32:47], v[234:237], v[4:7], v[32:47]
	ds_read_b128 v[234:237], v202 offset:41984
	s_waitcnt lgkmcnt(7)
	v_mfma_f32_32x32x16_bf16 v[16:31], v[238:241], v[4:7], v[16:31]
	ds_read_b128 v[238:241], v202 offset:42496
	v_fma_f32 v96, v96, s36, v3
	v_fma_f32 v97, v97, s36, v3
	v_fma_f32 v98, v98, s36, v3
	v_fma_f32 v99, v99, s36, v3
	v_fma_f32 v100, v100, s36, v3
	v_fma_f32 v101, v101, s36, v3
	v_fma_f32 v102, v102, s36, v3
	v_fma_f32 v103, v103, s36, v3
	v_exp_f32_e32 v96, v96
	v_exp_f32_e32 v97, v97
	v_exp_f32_e32 v98, v98
	v_exp_f32_e32 v99, v99
	v_exp_f32_e32 v100, v100
	v_exp_f32_e32 v101, v101
	v_exp_f32_e32 v102, v102
	v_exp_f32_e32 v103, v103
	v_cvt_pk_bf16_f32 v12, v96, v97
	v_cvt_pk_bf16_f32 v13, v98, v99
	v_cvt_pk_bf16_f32 v14, v100, v101
	v_cvt_pk_bf16_f32 v15, v102, v103
	s_waitcnt lgkmcnt(7)
	v_mfma_f32_32x32x16_bf16 v[32:47], v[242:245], v[8:11], v[32:47]
	ds_read_b128 v[242:245], v202 offset:46080
	s_waitcnt lgkmcnt(7)
	v_mfma_f32_32x32x16_bf16 v[16:31], v[246:249], v[8:11], v[16:31]
	ds_read_b128 v[246:249], v202 offset:46592
	v_fma_f32 v104, v104, s36, v3
	v_fma_f32 v105, v105, s36, v3
	v_fma_f32 v106, v106, s36, v3
	v_fma_f32 v107, v107, s36, v3
	v_fma_f32 v108, v108, s36, v3
	v_fma_f32 v109, v109, s36, v3
	v_fma_f32 v110, v110, s36, v3
	v_fma_f32 v111, v111, s36, v3
	v_exp_f32_e32 v104, v104
	v_exp_f32_e32 v105, v105
	v_exp_f32_e32 v106, v106
	v_exp_f32_e32 v107, v107
	v_exp_f32_e32 v108, v108
	v_exp_f32_e32 v109, v109
	v_exp_f32_e32 v110, v110
	v_exp_f32_e32 v111, v111
	v_cvt_pk_bf16_f32 v194, v104, v105
	v_cvt_pk_bf16_f32 v195, v106, v107
	v_cvt_pk_bf16_f32 v196, v108, v109
	v_cvt_pk_bf16_f32 v197, v110, v111
	s_nop 0
	s_waitcnt lgkmcnt(7)
	v_mfma_f32_32x32x16_bf16 v[64:79], v[218:221], v[12:15], v[64:79]
	s_waitcnt lgkmcnt(6)
	v_mfma_f32_32x32x16_bf16 v[48:63], v[222:225], v[12:15], v[48:63]
	v_add_f32_e32 v198, v80, v81
	v_add_f32_e32 v199, v82, v83
	v_add_f32_e32 v198, v198, v84
	v_add_f32_e32 v199, v199, v85
	v_add_f32_e32 v198, v198, v86
	v_add_f32_e32 v199, v199, v87
	v_add_f32_e32 v198, v198, v199
	s_waitcnt lgkmcnt(5)
	v_mfma_f32_32x32x16_bf16 v[64:79], v[226:229], v[194:197], v[64:79]
	s_waitcnt lgkmcnt(4)
	v_mfma_f32_32x32x16_bf16 v[48:63], v[230:233], v[194:197], v[48:63]
	v_add_f32_e32 v200, v88, v89
	v_add_f32_e32 v201, v90, v91
	v_add_f32_e32 v200, v200, v92
	v_add_f32_e32 v201, v201, v93
	v_add_f32_e32 v200, v200, v94
	v_add_f32_e32 v201, v201, v95
	v_add_f32_e32 v200, v200, v201
	s_waitcnt lgkmcnt(3)
	v_mfma_f32_32x32x16_bf16 v[32:47], v[234:237], v[12:15], v[32:47]
	s_waitcnt lgkmcnt(2)
	v_mfma_f32_32x32x16_bf16 v[16:31], v[238:241], v[12:15], v[16:31]
	v_add_f32_e32 v210, v96, v97
	v_add_f32_e32 v211, v98, v99
	v_add_f32_e32 v210, v210, v100
	v_add_f32_e32 v211, v211, v101
	v_add_f32_e32 v210, v210, v102
	v_add_f32_e32 v211, v211, v103
	v_add_f32_e32 v210, v210, v211
	s_waitcnt lgkmcnt(1)
	v_mfma_f32_32x32x16_bf16 v[32:47], v[242:245], v[194:197], v[32:47]
	v_add_f32_e32 v212, v104, v105
	v_add_f32_e32 v213, v106, v107
	v_add_f32_e32 v212, v212, v108
	v_add_f32_e32 v213, v213, v109
	v_add_f32_e32 v212, v212, v110
	v_add_f32_e32 v213, v213, v111
	v_add_f32_e32 v212, v212, v213
	s_waitcnt lgkmcnt(0)
	v_mfma_f32_32x32x16_bf16 v[16:31], v[246:249], v[194:197], v[16:31]
	v_add_f32_e32 v198, v198, v200
	v_add_f32_e32 v210, v210, v212
	v_add_f32_e32 v198, v198, v210
	v_mov_b32_e32 v1, v198
	s_nop 1
	v_permlane32_swap_b32_e32 v198, v1
	v_add_f32_e32 v1, v198, v1
	v_add_f32_e32 v190, v190, v1
	s_add_i32 s14, s14, 0x4000
	s_cmp_lg_u32 s14, 0x10000
	s_cbranch_scc1 .Lxa0_step
; __device__ __forceinline__ unsigned cvtpk(float lo, float hi) { f32x2v_ v = {lo, hi}; bf16x2v_ b = __builtin_convertvector(v, bf16x2v_); return __builtin_bit_cast(unsigned, b); }
; template <int DH>
; __device__ __forceinline__ void attn_store(bf16* orow, const f32x16 (&o)[DH / 32], float l_run, int h) {
;     const float il = 1.0f / l_run;
; #pragma unroll
;     for (int dg = 0; dg < DH / 32; ++dg)
; #pragma unroll
;         for (int g = 0; g < 4; g += 2) {
;             unsigned ax = cvtpk(o[dg][4 * g] * il, o[dg][4 * g + 1] * il), ay = cvtpk(o[dg][4 * g + 2] * il, o[dg][4 * g + 3] * il);
;             unsigned bx = cvtpk(o[dg][4 * g + 4] * il, o[dg][4 * g + 5] * il), by = cvtpk(o[dg][4 * g + 6] * il, o[dg][4 * g + 7] * il);
;             { auto rr = __builtin_amdgcn_permlane32_swap(ax, bx, false, false); ax = rr[0]; bx = rr[1]; }
;             { auto rr = __builtin_amdgcn_permlane32_swap(ay, by, false, false); ay = rr[0]; by = rr[1]; }
;             v4u w; w.x = ax; w.y = ay; w.z = bx; w.w = by;
;             *(v4u*)(orow + dg * 32 + 8 * g + 8 * h) = w; }
; }
; template <int l> __device__ __forceinline__ void layer_body(const Args& args, LAS unsigned char* lds, const XcdBarrier& bar) {
;     ...
;                 attn_store<128>(XO + (size_t)(q0g + r) * XAW + hd * 128, o, l_run, hh); } }
	s_add_u32 s10, s70, 0x11000000
	s_addc_u32 s11, s71, 0
	v_mov_b32_e32 v148, v144
	v_mov_b32_e32 v149, 0
	v_lshl_add_u64 v[148:149], v[148:149], 0, s[10:11]
	s_nop 7
	s_nop 7
	v_div_scale_f32 v1, s[10:11], v190, v190, 1.0
	v_rcp_f32_e32 v4, v1
	s_nop 0
	v_mov_b64_e32 v[8:9], v[148:149]
	s_nop 0
	v_fma_f32 v5, -v1, v4, 1.0
	v_fmac_f32_e32 v4, v5, v4
	v_div_scale_f32 v5, vcc, 1.0, v190, 1.0
	v_mul_f32_e32 v6, v5, v4
	v_fma_f32 v7, -v1, v6, v5
	v_fmac_f32_e32 v6, v7, v4
	v_fma_f32 v1, -v1, v6, v5
	v_div_fmas_f32 v1, v1, v4, v6
	v_div_fixup_f32 v6, v1, v190, 1.0
	v_pk_mul_f32 v[2:3], v[64:65], v[6:7] op_sel_hi:[1,0]
	v_pk_mul_f32 v[4:5], v[66:67], v[6:7] op_sel_hi:[1,0]
	v_cvt_pk_bf16_f32 v2, v2, v3
	v_cvt_pk_bf16_f32 v3, v4, v5
	v_pk_mul_f32 v[4:5], v[68:69], v[6:7] op_sel_hi:[1,0]
	v_pk_mul_f32 v[10:11], v[70:71], v[6:7] op_sel_hi:[1,0]
	v_cvt_pk_bf16_f32 v4, v4, v5
	v_cvt_pk_bf16_f32 v5, v10, v11
	s_nop 0
	v_permlane32_swap_b32_e32 v2, v4
	v_permlane32_swap_b32_e32 v3, v5
	global_store_dwordx4 v[8:9], v[2:5], off
	v_pk_mul_f32 v[10:11], v[78:79], v[6:7] op_sel_hi:[1,0]
	s_nop 0
	v_pk_mul_f32 v[2:3], v[72:73], v[6:7] op_sel_hi:[1,0]
	v_pk_mul_f32 v[4:5], v[74:75], v[6:7] op_sel_hi:[1,0]
	v_cvt_pk_bf16_f32 v2, v2, v3
	v_cvt_pk_bf16_f32 v3, v4, v5
	v_pk_mul_f32 v[4:5], v[76:77], v[6:7] op_sel_hi:[1,0]
	s_nop 0
	v_cvt_pk_bf16_f32 v4, v4, v5
	v_cvt_pk_bf16_f32 v5, v10, v11
	s_nop 0
	v_permlane32_swap_b32_e32 v2, v4
	v_permlane32_swap_b32_e32 v3, v5
	global_store_dwordx4 v[8:9], v[2:5], off offset:32
	v_pk_mul_f32 v[10:11], v[54:55], v[6:7] op_sel_hi:[1,0]
	s_nop 0
	v_pk_mul_f32 v[2:3], v[48:49], v[6:7] op_sel_hi:[1,0]
	v_pk_mul_f32 v[4:5], v[50:51], v[6:7] op_sel_hi:[1,0]
	v_cvt_pk_bf16_f32 v2, v2, v3
	v_cvt_pk_bf16_f32 v3, v4, v5
	v_pk_mul_f32 v[4:5], v[52:53], v[6:7] op_sel_hi:[1,0]
	s_nop 0
	v_cvt_pk_bf16_f32 v4, v4, v5
	v_cvt_pk_bf16_f32 v5, v10, v11
	s_nop 0
	v_permlane32_swap_b32_e32 v2, v4
	v_permlane32_swap_b32_e32 v3, v5
	global_store_dwordx4 v[8:9], v[2:5], off offset:64
	v_pk_mul_f32 v[10:11], v[62:63], v[6:7] op_sel_hi:[1,0]
	s_nop 0
	v_pk_mul_f32 v[2:3], v[56:57], v[6:7] op_sel_hi:[1,0]
	v_pk_mul_f32 v[4:5], v[58:59], v[6:7] op_sel_hi:[1,0]
	v_cvt_pk_bf16_f32 v2, v2, v3
	v_cvt_pk_bf16_f32 v3, v4, v5
	v_pk_mul_f32 v[4:5], v[60:61], v[6:7] op_sel_hi:[1,0]
	s_nop 0
	v_cvt_pk_bf16_f32 v4, v4, v5
	v_cvt_pk_bf16_f32 v5, v10, v11
	s_nop 0
	v_permlane32_swap_b32_e32 v2, v4
	v_permlane32_swap_b32_e32 v3, v5
	global_store_dwordx4 v[8:9], v[2:5], off offset:96
	v_pk_mul_f32 v[10:11], v[38:39], v[6:7] op_sel_hi:[1,0]
	s_nop 0
	v_pk_mul_f32 v[2:3], v[32:33], v[6:7] op_sel_hi:[1,0]
	v_pk_mul_f32 v[4:5], v[34:35], v[6:7] op_sel_hi:[1,0]
	v_cvt_pk_bf16_f32 v2, v2, v3
	v_cvt_pk_bf16_f32 v3, v4, v5
	v_pk_mul_f32 v[4:5], v[36:37], v[6:7] op_sel_hi:[1,0]
	s_nop 0
	v_cvt_pk_bf16_f32 v4, v4, v5
	v_cvt_pk_bf16_f32 v5, v10, v11
	s_nop 0
	v_permlane32_swap_b32_e32 v2, v4
	v_permlane32_swap_b32_e32 v3, v5
	global_store_dwordx4 v[8:9], v[2:5], off offset:128
	v_pk_mul_f32 v[10:11], v[46:47], v[6:7] op_sel_hi:[1,0]
	s_nop 0
	v_pk_mul_f32 v[2:3], v[40:41], v[6:7] op_sel_hi:[1,0]
	v_pk_mul_f32 v[4:5], v[42:43], v[6:7] op_sel_hi:[1,0]
	v_cvt_pk_bf16_f32 v2, v2, v3
	v_cvt_pk_bf16_f32 v3, v4, v5
	v_pk_mul_f32 v[4:5], v[44:45], v[6:7] op_sel_hi:[1,0]
	s_nop 0
	v_cvt_pk_bf16_f32 v4, v4, v5
	v_cvt_pk_bf16_f32 v5, v10, v11
	s_nop 0
	v_permlane32_swap_b32_e32 v2, v4
	v_permlane32_swap_b32_e32 v3, v5
	global_store_dwordx4 v[8:9], v[2:5], off offset:160
	v_pk_mul_f32 v[10:11], v[22:23], v[6:7] op_sel_hi:[1,0]
	s_nop 0
	v_pk_mul_f32 v[2:3], v[16:17], v[6:7] op_sel_hi:[1,0]
	v_pk_mul_f32 v[4:5], v[18:19], v[6:7] op_sel_hi:[1,0]
	v_cvt_pk_bf16_f32 v2, v2, v3
	v_cvt_pk_bf16_f32 v3, v4, v5
	v_pk_mul_f32 v[4:5], v[20:21], v[6:7] op_sel_hi:[1,0]
	s_nop 0
	v_cvt_pk_bf16_f32 v4, v4, v5
	v_cvt_pk_bf16_f32 v5, v10, v11
	s_nop 0
	v_permlane32_swap_b32_e32 v2, v4
	v_permlane32_swap_b32_e32 v3, v5
	global_store_dwordx4 v[8:9], v[2:5], off offset:192
	s_nop 1
	v_pk_mul_f32 v[2:3], v[24:25], v[6:7] op_sel_hi:[1,0]
	v_pk_mul_f32 v[4:5], v[26:27], v[6:7] op_sel_hi:[1,0]
	v_cvt_pk_bf16_f32 v2, v2, v3
	v_cvt_pk_bf16_f32 v3, v4, v5
	v_pk_mul_f32 v[4:5], v[28:29], v[6:7] op_sel_hi:[1,0]
	v_pk_mul_f32 v[6:7], v[30:31], v[6:7] op_sel_hi:[1,0]
	v_cvt_pk_bf16_f32 v4, v4, v5
	v_cvt_pk_bf16_f32 v5, v6, v7
	s_nop 0
	v_permlane32_swap_b32_e32 v2, v4
	v_permlane32_swap_b32_e32 v3, v5
	global_store_dwordx4 v[8:9], v[2:5], off offset:224
	s_add_i32 s3, s3, 1
	s_cmp_lg_u32 s3, 2
	s_cbranch_scc1 .Lxa0_jj

; template <int l> __device__ __forceinline__ void layer_body(const Args& args, LAS unsigned char* lds, const XcdBarrier& bar) {
;     ...
;         { const int hd = wave & 3; const float scale2 = 0.08838834764831845f * LOG2E;
;           for (int rep = 0; rep < NREP(7); ++rep) for (int w = bx; w < T / 128; w += G)
;             for (int jj = 0; jj < 2; ++jj) { const int qt = w * 4 + (wave >> 2) * 2 + jj, b = qt >> 7, q0g = qt * 32;
;                 bf16x8 qf[8];
; #pragma unroll
;                 for (int s = 0; s < 8; ++s) qf[s] = *(const bf16x8*)(XQ + (size_t)(q0g + r) * XAW + hd * 128 + 16 * s + 8 * hh);
;                 f32x16 o[4];
; #pragma unroll
;                 for (int dg = 0; dg < 4; ++dg)
; #pragma unroll
;                     for (int i = 0; i < 16; ++i) o[dg][i] = 0.f;
;                 float m_run = -1e30f, l_run = 0.f;
;                 const size_t tb0 = ((size_t)l * 32 + b * 4 + hd) * 8 * 4096;
;                 attn_run<128>(XKP + tb0 + (hh * 32 + pr) * 8, XVP + tb0 + (hh * 128 + r) * 8, 0, 7, qf, o, m_run, l_run, [&](int t, f32x16& st) {
.LBB0_1740:
	s_or_b64 exec, exec, s[0:1]
	s_and_b64 vcc, exec, s[6:7]
	s_waitcnt lgkmcnt(0)
	s_barrier
	s_cbranch_vccnz .LBB0_1749
	v_readfirstlane_b32 s3, v204
	s_and_b32 s0, s2, 3
	s_lshr_b32 s3, s3, 6
	s_lshr_b32 s1, s2, 2
	s_lshl_b32 s15, s1, 4
	s_lshl_b32 s37, s3, 1
	s_add_i32 s15, s15, s37
	s_lshr_b32 s1, s15, 7
	s_lshl_b32 s1, s1, 2
	s_add_i32 s1, s1, s0
	s_add_i32 s1, s1, 32
	s_lshl_b32 s1, s1, 16
	s_lshl_b32 s37, s3, 13
	s_add_i32 s1, s1, s37
	s_mov_b32 s36, 0x3e0293ee
	v_and_b32_e32 v2, 63, v204
	v_mov_b32_e32 v7, 0
	v_and_b32_e32 v3, 31, v2
	v_lshrrev_b32_e32 v4, 5, v2
	v_and_b32_e32 v5, 19, v3
	v_and_b32_e32 v6, 4, v3
	v_lshlrev_b32_e32 v6, 1, v6
	v_and_b32_e32 v8, 8, v3
	v_lshrrev_b32_e32 v8, 1, v8
	v_or3_b32 v5, v5, v6, v8
	v_lshl_add_u32 v5, v4, 5, v5
	v_lshlrev_b32_e32 v145, 4, v5
	v_lshl_add_u32 v6, v4, 7, v3
	v_lshlrev_b32_e32 v179, 4, v6
	v_add_u32_e32 v179, 0x8000, v179
	v_mov_b32_e32 v6, v2
	v_lshlrev_b32_e32 v146, 10, v3
	v_lshl_add_u32 v146, v4, 4, v146
	s_add_u32 s10, s70, 0x6800000
	s_addc_u32 s11, s71, 0
	s_add_u32 s10, s10, s1
	s_addc_u32 s11, s11, 0
	v_lshl_add_u64 v[8:9], v[6:7], 4, s[10:11]
	s_mov_b64 s[10:11], 0x1000
	v_lshl_add_u64 v[10:11], v[8:9], 0, s[10:11]
	s_mov_b64 s[10:11], 0x400000
	v_lshl_add_u64 v[12:13], v[8:9], 0, s[10:11]
	v_lshl_add_u64 v[14:15], v[10:11], 0, s[10:11]
	s_mov_b32 m0, s37
	s_nop 0
	global_load_lds_dwordx4 v[8:9], off
	global_load_lds_dwordx4 v[8:9], off offset:1024
	global_load_lds_dwordx4 v[8:9], off offset:2048
	global_load_lds_dwordx4 v[8:9], off offset:3072
	s_add_i32 m0, s37, 0x1000
	s_nop 0
	global_load_lds_dwordx4 v[10:11], off
	global_load_lds_dwordx4 v[10:11], off offset:1024
	global_load_lds_dwordx4 v[10:11], off offset:2048
	global_load_lds_dwordx4 v[10:11], off offset:3072
	s_add_i32 m0, s37, 0x10000
	s_nop 0
	global_load_lds_dwordx4 v[12:13], off
	global_load_lds_dwordx4 v[12:13], off offset:1024
	global_load_lds_dwordx4 v[12:13], off offset:2048
	global_load_lds_dwordx4 v[12:13], off offset:3072
	s_add_i32 m0, s37, 0x11000
	s_nop 0
	global_load_lds_dwordx4 v[14:15], off
	global_load_lds_dwordx4 v[14:15], off offset:1024
	global_load_lds_dwordx4 v[14:15], off offset:2048
	global_load_lds_dwordx4 v[14:15], off offset:3072
	s_lshl_b32 s0, s0, 8
	s_mov_b32 s3, 0
